# EpiResid GEMM phases: workgroups owning a context part-K unit run it first, so the two halves of the grid reach the residual epilogues at different times
# baseline (speedup 1.0000x reference)
.LBB0_482:
	s_and_b64 s[34:35], s[6:7], exec
	s_cselect_b32 s21, 0x80, 0
	s_cmp_lt_u32 s20, s21
	s_cselect_b32 s21, 0x200, 0
	s_add_i32 s20, s20, s21
	s_cmpk_lt_i32 s20, 0x200
	s_cselect_b64 s[54:55], -1, 0
	s_cmpk_gt_i32 s20, 0x1ff
	s_cselect_b64 s[2:3], -1, 0
	s_and_b64 s[34:35], s[2:3], exec
	s_cselect_b32 s10, 0, s20
	s_ashr_i32 s21, s10, 31
	s_lshr_b32 s21, s21, 29
	s_add_i32 s35, s10, s21
	s_and_b32 s21, s35, -8
	s_sub_i32 s10, s10, s21
	v_readfirstlane_b32 s19, v160
	s_cmp_gt_i32 s10, -1
	s_mov_b64 s[60:61], -1
	s_cbranch_scc0 .LBB0_484
	s_lshl_b32 s44, s10, 6
	s_mov_b64 s[60:61], 0

.LBB0_493:
	s_cmp_gt_i32 s20, -1
	s_cselect_b64 s[54:55], -1, 0
	s_cmpk_lt_i32 s20, 0x200
	s_cselect_b32 s21, 0, 0x200
	s_sub_i32 s20, s20, s21
	s_and_b64 s[6:7], s[54:55], s[6:7]
	s_andn2_b64 vcc, exec, s[6:7]
	s_cbranch_vccnz .LBB0_522
	s_waitcnt vmcnt(0) lgkmcnt(0)
	v_bfe_i32 v1, v160, 27, 1
	v_lshlrev_b32_e32 v3, 4, v160
	v_lshrrev_b32_e32 v1, 22, v1
	v_add_u32_e32 v1, v3, v1
	v_and_b32_e32 v1, 0xfffffc00, v1
	v_sub_u32_e32 v1, v3, v1
	v_lshrrev_b32_e32 v2, 4, v1
	v_bitop3_b32 v1, v2, v1, 32 bitop3:0x6c
	v_ashrrev_i32_e32 v0, 31, v160
	v_ashrrev_i32_e32 v4, 31, v1
	v_lshrrev_b32_e32 v0, 26, v0
	v_lshrrev_b32_e32 v4, 26, v4
	v_add_u32_e32 v0, v160, v0
	v_add_u32_e32 v4, v1, v4
	v_ashrrev_i32_e32 v0, 6, v0
	v_ashrrev_i32_e32 v5, 6, v4
	v_and_b32_e32 v4, 0xc0, v4
	v_lshlrev_b32_e32 v2, 3, v0
	v_sub_u32_e32 v1, v1, v4
	v_and_b32_e32 v2, 0x7ffffff0, v2
	v_lshlrev_b32_e32 v0, 5, v0
	v_ashrrev_i16_sdwa v1, v196, sext(v1) dst_sel:DWORD dst_unused:UNUSED_PAD src0_sel:DWORD src1_sel:BYTE_0
	v_add_u32_e32 v2, v5, v2
	v_and_b32_e32 v0, 32, v0
	v_bfe_i32 v1, v1, 0, 16
	v_mul_lo_u32 v2, s25, v2
	v_add_u32_e32 v4, v0, v1
	v_add_u32_e32 v3, 0x2000, v3
	v_add_lshl_u32 v156, v4, v2, 1
	v_ashrrev_i32_e32 v4, 31, v3
	v_lshrrev_b32_e32 v4, 22, v4
	v_add_u32_e32 v4, v3, v4
	v_ashrrev_i32_e32 v4, 10, v4
	v_mul_i32_i24_e32 v5, 0x400, v4
	v_sub_u32_e32 v3, v3, v5
	v_lshrrev_b32_e32 v5, 4, v3
	v_bitop3_b32 v5, v5, v3, 32 bitop3:0x6c
	v_ashrrev_i32_e32 v6, 31, v5
	v_lshrrev_b32_e32 v6, 26, v6
	v_lshlrev_b32_e32 v3, 3, v4
	v_add_u32_e32 v6, v5, v6
	s_ashr_i32 s77, s19, 6
	s_lshl_b32 s45, s25, 9
	s_ashr_i32 s73, s19, 8
	v_and_b32_e32 v3, 0x7ffffff0, v3
	v_ashrrev_i32_e32 v7, 6, v6
	s_lshl_b32 s54, s25, 8
	s_lshl_b32 s53, s77, 10
	s_mul_i32 s7, s45, s85
	v_add_u32_e32 v7, v7, v3
	v_lshlrev_b32_e32 v3, 5, v4
	v_and_b32_e32 v4, 0xc0, v6
	s_mul_hi_i32 s6, s45, s85
	s_add_u32 s21, s48, s7
	v_sub_u32_e32 v4, v5, v4
	v_mul_lo_u32 v5, s25, v7
	s_addc_u32 s25, s49, s6
	s_mul_i32 s7, s45, s24
	s_mul_hi_i32 s6, s45, s24
	s_add_u32 s7, s40, s7
	s_addc_u32 s47, s41, s6
	s_add_u32 s6, s7, s2
	v_ashrrev_i16_sdwa v4, v196, sext(v4) dst_sel:DWORD dst_unused:UNUSED_PAD src0_sel:DWORD src1_sel:BYTE_0
	s_addc_u32 s7, s47, s3
	s_add_i32 s88, s53, 0
	v_and_b32_e32 v3, 32, v3
	v_bfe_i32 v4, v4, 0, 16
	s_add_i32 m0, s88, 0x10000
	v_add_u32_e32 v6, v3, v4
	global_load_lds_dwordx4 v156, s[6:7]
	s_add_i32 m0, s88, 0x12000
	v_add_lshl_u32 v162, v6, v5, 1
	s_add_u32 s60, s21, s2
	global_load_lds_dwordx4 v162, s[6:7]
	s_addc_u32 s61, s25, s3
	s_mov_b32 m0, s88
	s_add_i32 s89, s88, 0x2000
	global_load_lds_dwordx4 v156, s[60:61]
	s_mov_b32 m0, s89
	s_add_u32 s2, s6, s54
	global_load_lds_dwordx4 v162, s[60:61]
	s_addc_u32 s3, s7, 0
	s_add_i32 m0, s88, 0x14000
	v_mov_b32_e32 v252, 0x3e16c740
	global_load_lds_dwordx4 v156, s[2:3]
	s_add_i32 m0, s88, 0x16000
	s_add_u32 s62, s60, s54
	s_addc_u32 s63, s61, 0
	s_add_i32 s94, s88, 0x4000
	global_load_lds_dwordx4 v162, s[2:3]
	s_mov_b32 m0, s94
	s_add_i32 s95, s88, 0x6000
	global_load_lds_dwordx4 v156, s[62:63]
	s_mov_b32 m0, s95
	s_cmp_lg_u32 s73, 1
	global_load_lds_dwordx4 v162, s[62:63]
	s_load_dwordx2 s[62:63], s[38:39], 0x0
	s_load_dwordx2 s[66:67], s[0:1], 0xd0
	s_mov_b32 s55, s11
	s_cbranch_scc1 .LBB0_496
	s_barrier

.LBB0_498:
	s_add_i32 s55, s55, 1
	s_mul_i32 s25, s55, s18
	s_add_i32 s25, s25, s20
	s_add_i32 s92, s34, 0xfffffe00
	s_cmp_lt_i32 s20, s92
	s_cselect_b32 s21, s18, 0
	s_cselect_b32 s92, 0x200, s34
	s_sub_i32 s25, s25, s21
	s_cmpk_lt_i32 s25, 0x200
	s_cselect_b64 s[38:39], -1, 0
	s_cmpk_gt_i32 s25, 0x1ff
	s_cselect_b64 s[2:3], -1, 0
	s_and_b64 s[78:79], s[2:3], exec
	s_cselect_b32 s21, 0, s25
	s_ashr_i32 s73, s21, 31
	s_lshr_b32 s73, s73, 29
	s_add_i32 s93, s21, s73
	s_and_b32 s73, s93, -8
	s_sub_i32 s73, s21, s73
	s_cmp_gt_i32 s73, -1
	s_mov_b64 s[78:79], -1
	s_cbranch_scc0 .LBB0_500
	s_lshl_b32 s21, s73, 6
	s_mov_b64 s[78:79], 0

.LBB0_502:
	s_cmp_lt_i32 s25, s92
	s_cselect_b64 s[80:81], -1, 0
	s_cmp_ge_i32 s25, s92
	s_cselect_b64 s[78:79], -1, 0
	s_and_b64 s[82:83], s[2:3], s[80:81]
	s_addk_i32 s25, 0xfe00
	s_and_b64 s[82:83], s[82:83], exec
	s_cselect_b32 s92, s25, 0
	s_mov_b64 s[82:83], -1
	s_and_b64 vcc, exec, s[38:39]
	s_cbranch_vccnz .LBB0_506
	s_andn2_b64 vcc, exec, s[82:83]
	s_cbranch_vccz .LBB0_507
